# prep loop: L2 prefetch of row t+3 combined with a latch wait that covers only the loads (vmcnt(9))
# baseline (speedup 1.0000x reference)
.LBB0_873:
	v_mov_b64_e32 v[100:101], v[104:105]
	v_mov_b64_e32 v[102:103], v[106:107]
	v_mov_b64_e32 v[104:105], v[112:113]
	v_mov_b64_e32 v[106:107], v[114:115]
	v_mov_b64_e32 v[112:113], v[132:133]
	v_mov_b64_e32 v[114:115], v[134:135]
	v_mov_b64_e32 v[132:133], v[144:145]
	s_add_i32 s100, s5, 3
	v_readlane_b32 s101, v253, 16
	s_add_i32 s101, s101, -1
	s_min_u32 s100, s100, s101
	v_add_u32_e32 v236, s100, v148
	v_mov_b32_e32 v237, 0
	v_mul_u32_u24_e32 v238, 48, v224
	v_lshlrev_b64 v[236:237], 12, v[236:237]
	v_mov_b32_e32 v239, 0
	v_lshl_add_u64 v[236:237], v[2:3], 0, v[236:237]
	v_lshl_add_u64 v[236:237], v[236:237], 0, v[238:239]
	global_load_dword v240, v[236:237], off
	s_waitcnt vmcnt(9)
	v_mov_b64_e32 v[108:109], v[116:117]
	s_and_b64 vcc, exec, s[8:9]
	v_mov_b64_e32 v[134:135], v[146:147]
	v_mov_b64_e32 v[212:213], v[196:197]
	v_mov_b64_e32 v[208:209], v[192:193]
	v_mov_b64_e32 v[204:205], v[188:189]
	v_mov_b64_e32 v[200:201], v[184:185]
	v_mov_b64_e32 v[214:215], v[198:199]
	v_mov_b64_e32 v[210:211], v[194:195]
	v_mov_b64_e32 v[206:207], v[190:191]
	v_mov_b64_e32 v[202:203], v[186:187]
	s_mov_b32 s5, s4
	v_mov_b64_e32 v[110:111], v[118:119]
	v_mov_b32_e32 v144, v128
	v_mov_b32_e32 v145, v129
	v_mov_b32_e32 v146, v130
	v_mov_b32_e32 v147, v131
	v_mov_b32_e32 v140, v124
	v_mov_b32_e32 v141, v125
	v_mov_b32_e32 v142, v126
	v_mov_b32_e32 v143, v127
	v_mov_b32_e32 v136, v120
	v_mov_b32_e32 v137, v121
	v_mov_b32_e32 v138, v122
	v_mov_b32_e32 v139, v123
	v_mov_b32_e32 v216, v116
	v_mov_b32_e32 v217, v117
	v_mov_b32_e32 v218, v118
	v_mov_b32_e32 v219, v119
	s_cbranch_vccnz .LBB0_895
